# wkv chunk-summary output blocks (32 basic blocks in the item loop): LDS operand reads hoisted to the block top into spare registers v80-v119, waits recomputed
# speedup vs baseline: 1.0071x; 1.0030x over previous
.LBB0_830:
	s_or_b64 exec, exec, s[0:1]
	v_lshlrev_b32_e32 v40, 5, v135
	v_add3_u32 v72, s97, v40, v60
	ds_read_b64 v[40:41], v72
	v_mov_b32_e32 v42, v43
	v_cvt_pk_bf16_f32 v52, v52, v53
	v_cvt_pk_bf16_f32 v53, v54, v55
	v_mov_b32_e32 v54, v43
	v_mov_b32_e32 v55, v43
	v_add3_u32 v73, v68, v63, v60
	s_mov_b32 s0, 0xfc00
	v_add3_u32 v62, v62, v63, s0
	s_waitcnt lgkmcnt(0)
	v_mfma_f32_16x16x32_bf16 v[52:55], v[40:43], v[52:55], 0
	v_add_u32_e32 v76, v73, v74
	v_lshlrev_b32_e32 v61, 3, v138
	s_movk_i32 s0, 0x7f
	s_ashr_i32 s77, s76, 31
	v_cmp_lt_u32_e32 vcc, s0, v137
	s_nop 2
	v_cvt_pk_bf16_f32 v40, v52, v53
	v_cvt_pk_bf16_f32 v41, v54, v55
	ds_write_b64 v73, v[40:41]
	ds_read_b128 v[52:55], v62 offset:2304
	ds_read_b128 v[68:71], v76
	ds_read_b64 v[40:41], v72 offset:512
	s_waitcnt lgkmcnt(1)
	v_mfma_f32_16x16x32_bf16 v[52:55], v[52:55], v[68:71], v[56:59]
	s_lshl_b64 s[6:7], s[76:77], 13
	s_nop 6
	v_cvt_pk_bf16_f32 v52, v52, v53
	v_cvt_pk_bf16_f32 v53, v54, v55
	v_mov_b32_e32 v54, v43
	v_mov_b32_e32 v55, v43
	s_waitcnt lgkmcnt(0)
	s_nop 0
	v_mfma_f32_16x16x32_bf16 v[52:55], v[40:43], v[52:55], 0
	s_nop 7
	v_cvt_pk_bf16_f32 v40, v52, v53
	v_cvt_pk_bf16_f32 v41, v54, v55
	ds_write_b64 v73, v[40:41] offset:32
	ds_read_b128 v[52:55], v62 offset:4608
	ds_read_b128 v[56:59], v76
	ds_read_b64 v[40:41], v72 offset:1024
	s_waitcnt lgkmcnt(1)
	v_mfma_f32_16x16x32_bf16 v[48:51], v[52:55], v[56:59], v[48:51]
	s_nop 7
	v_cvt_pk_bf16_f32 v48, v48, v49
	v_cvt_pk_bf16_f32 v49, v50, v51
	v_mov_b32_e32 v50, v43
	v_mov_b32_e32 v51, v43
	s_waitcnt lgkmcnt(0)
	s_nop 0
	v_mfma_f32_16x16x32_bf16 v[48:51], v[40:43], v[48:51], 0
	s_nop 7
	v_cvt_pk_bf16_f32 v40, v48, v49
	v_cvt_pk_bf16_f32 v41, v50, v51
	ds_write_b64 v73, v[40:41] offset:64
	ds_read_b128 v[48:51], v62 offset:6912
	s_waitcnt lgkmcnt(0)
	v_mfma_f32_16x16x32_bf16 v[44:47], v[48:51], v[56:59], v[44:47]
	ds_read_b128 v[48:51], v62 offset:6976
	ds_read_b128 v[52:55], v76 offset:64
	ds_read_b64 v[40:41], v72 offset:1536
	v_and_b32_e32 v59, 8, v61
	s_waitcnt lgkmcnt(1)
	v_mfma_f32_16x16x32_bf16 v[44:47], v[48:51], v[52:55], v[44:47]
	v_lshl_add_u32 v48, v67, 1, 0
	v_mul_i32_i24_e32 v50, 0x48, v66
	v_ashrrev_i32_e32 v55, 7, v137
	s_nop 4
	v_cvt_pk_bf16_f32 v44, v44, v45
	v_cvt_pk_bf16_f32 v45, v46, v47
	v_mov_b32_e32 v46, v43
	v_mov_b32_e32 v47, v43
	v_lshl_add_u32 v49, v50, 1, v48
	v_add_u32_e32 v53, v48, v65
	s_waitcnt lgkmcnt(0)
	v_mfma_f32_16x16x32_bf16 v[44:47], v[40:43], v[44:47], 0
	s_nop 7
	v_cvt_pk_bf16_f32 v40, v44, v45
	v_cvt_pk_bf16_f32 v41, v46, v47
	ds_write_b64 v73, v[40:41] offset:96
	s_waitcnt lgkmcnt(0)
	s_barrier
	v_lshlrev_b32_e32 v41, 1, v74
	v_lshlrev_b32_e32 v40, 1, v64
	v_add_u32_e32 v56, s94, v41
	v_add_u32_e32 v52, s33, v41
	v_add_u32_e32 v51, s90, v40
	v_add_u32_e32 v57, s90, v41
	v_add_u32_e32 v54, s95, v40
	v_lshlrev_b32_e32 v41, 2, v59
	s_and_saveexec_b64 s[0:1], vcc
	s_xor_b64 s[8:9], exec, s[0:1]
	s_cbranch_execz .LBB0_842
	v_cmp_lt_i32_e64 s[0:1], 1, v55
	s_mov_b64 s[76:77], 0
	s_mov_b64 s[84:85], 0
	s_and_saveexec_b64 s[24:25], s[0:1]
	s_xor_b64 s[80:81], exec, s[24:25]
	s_cbranch_execz .LBB0_837
	v_cmp_eq_u32_e64 s[0:1], 2, v55
	s_mov_b64 s[86:87], -1
	s_and_saveexec_b64 s[84:85], s[0:1]
	s_cbranch_execz .LBB0_834
	v_or_b32_e32 v80, v41, v135
	v_mul_u32_u24_e32 v81, 0x48, v135
	v_mad_u32_u24 v82, v80, s96, v56
	v_lshlrev_b32_e32 v80, 1, v81
	v_add_u32_e32 v81, v52, v80
	ds_read_b128 v[84:87], v82
	ds_read_b128 v[88:91], v81
	ds_read_b128 v[92:95], v82 offset:64
	ds_read_b128 v[96:99], v81 offset:64
	s_waitcnt lgkmcnt(2)
	v_mfma_f32_16x16x32_bf16 v[44:47], v[84:87], v[88:91], 0
	v_lshlrev_b32_e32 v66, 1, v41
	v_add_u32_e32 v81, 0, v80
	v_add3_u32 v80, v81, v66, v74
	ds_read_b64 v[82:83], v80 offset:27648
	s_waitcnt lgkmcnt(1)
	v_mfma_f32_16x16x32_bf16 v[44:47], v[92:95], v[96:99], v[44:47]
	s_add_u32 s0, s58, s6
	s_addc_u32 s1, s59, s7
	v_lshlrev_b32_e32 v42, 1, v75
	s_waitcnt lgkmcnt(0)
	v_and_b32_e32 v71, 0xffff0000, v82
	v_lshlrev_b32_e32 v70, 16, v82
	s_nop 1
	v_pk_add_f32 v[44:45], v[44:45], v[70:71]
	v_and_b32_e32 v71, 0xffff0000, v83
	v_lshlrev_b32_e32 v70, 16, v83
	v_pk_add_f32 v[46:47], v[46:47], v[70:71]
	v_cvt_pk_bf16_f32 v44, v44, v45
	v_cvt_pk_bf16_f32 v45, v46, v47
	v_lshl_add_u64 v[46:47], s[0:1], 0, v[42:43]
	v_mov_b32_e32 v67, v43
	v_lshl_add_u64 v[46:47], v[46:47], 0, v[66:67]
	s_xor_b64 s[86:87], exec, -1

.LBB0_836:
	v_or_b32_e32 v80, v41, v135
	v_mad_u32_u24 v81, v80, s96, v57
	v_add_u32_e32 v80, v52, v63
	ds_read_b128 v[84:87], v81
	ds_read_b128 v[88:91], v80
	ds_read_b128 v[92:95], v81 offset:64
	ds_read_b128 v[96:99], v80 offset:64
	s_waitcnt lgkmcnt(2)
	v_mfma_f32_16x16x32_bf16 v[44:47], v[84:87], v[88:91], 0
	s_add_u32 s24, s60, s6
	s_addc_u32 s25, s61, s7
	s_andn2_b64 s[76:77], s[76:77], exec
	s_waitcnt lgkmcnt(0)
	v_mfma_f32_16x16x32_bf16 v[44:47], v[92:95], v[96:99], v[44:47]
	v_lshlrev_b32_e32 v76, 1, v41
	v_add_u32_e32 v80, v54, v63
	v_add_u32_e32 v81, v53, v76
	ds_read_b64_tr_b16 v[84:85], v81 offset:55296
	ds_read_b64_tr_b16 v[86:87], v81 offset:55872
	ds_read_b128 v[88:91], v80
	ds_read_b64_tr_b16 v[92:93], v81 offset:59904
	ds_read_b64_tr_b16 v[94:95], v81 offset:60480
	ds_read_b128 v[96:99], v80 offset:64
	v_mov_b32_e32 v77, v43
	s_waitcnt lgkmcnt(3)
	v_mfma_f32_16x16x32_bf16 v[44:47], v[84:87], v[88:91], v[44:47]
	v_lshlrev_b32_e32 v42, 1, v75
	s_waitcnt lgkmcnt(0)
	v_mfma_f32_16x16x32_bf16 v[44:47], v[92:95], v[96:99], v[44:47]
	s_nop 7
	v_cvt_pk_bf16_f32 v44, v44, v45
	v_cvt_pk_bf16_f32 v45, v46, v47
	v_lshl_add_u64 v[46:47], s[24:25], 0, v[42:43]
	v_lshl_add_u64 v[46:47], v[46:47], 0, v[76:77]
	s_or_b64 exec, exec, s[0:1]
	s_and_saveexec_b64 s[0:1], s[76:77]
	s_cbranch_execnz .LBB0_840
	s_branch .LBB0_841

.LBB0_840:
	v_lshlrev_b32_e32 v76, 1, v41
	v_add_u32_e32 v80, v49, v76
	v_add_u32_e32 v81, v51, v63
	ds_read_b64_tr_b16 v[84:85], v80 offset:36864
	ds_read_b64_tr_b16 v[86:87], v80 offset:37440
	ds_read_b128 v[88:91], v81
	ds_read_b64_tr_b16 v[92:93], v80 offset:41472
	ds_read_b64_tr_b16 v[94:95], v80 offset:42048
	ds_read_b128 v[96:99], v81 offset:64
	v_lshlrev_b32_e32 v80, 3, v59
	v_lshlrev_b32_e32 v81, 1, v50
	v_add3_u32 v82, v48, v80, v81
	ds_read_b64_tr_b16 v[100:101], v82 offset:46080
	ds_read_b64_tr_b16 v[102:103], v82 offset:46656
	ds_read_b64_tr_b16 v[104:105], v49 offset:55296
	ds_read_b64_tr_b16 v[106:107], v49 offset:55872
	ds_read_b64_tr_b16 v[108:109], v82 offset:50688
	s_add_u32 s24, s56, s6
	s_addc_u32 s25, s57, s7
	v_mov_b32_e32 v77, v43
	s_waitcnt lgkmcnt(8)
	v_mfma_f32_16x16x32_bf16 v[44:47], v[84:87], v[88:91], 0
	ds_read_b64_tr_b16 v[110:111], v82 offset:51264
	ds_read_b64_tr_b16 v[80:81], v49 offset:59904
	ds_read_b64_tr_b16 v[82:83], v49 offset:60480
	s_waitcnt lgkmcnt(8)
	v_mfma_f32_16x16x32_bf16 v[44:47], v[92:95], v[96:99], v[44:47]
	s_waitcnt lgkmcnt(4)
	v_mfma_f32_16x16x32_bf16 v[44:47], v[100:103], v[104:107], v[44:47]
	v_lshlrev_b32_e32 v42, 1, v75
	s_waitcnt lgkmcnt(0)
	v_mfma_f32_16x16x32_bf16 v[44:47], v[108:111], v[80:83], v[44:47]
	s_nop 7
	v_cvt_pk_bf16_f32 v44, v44, v45
	v_cvt_pk_bf16_f32 v45, v46, v47
	v_lshl_add_u64 v[46:47], s[24:25], 0, v[42:43]
	v_lshl_add_u64 v[46:47], v[46:47], 0, v[76:77]

.LBB0_842:
	s_or_saveexec_b64 s[0:1], s[8:9]
	v_add_u32_e32 v62, s94, v40
	v_and_b32_e32 v40, 24, v136
	v_add_u32_e32 v40, 0, v40
	v_or_b32_e32 v64, v41, v135
	v_add_u32_e32 v58, v40, v65
	v_lshlrev_b32_e32 v40, 1, v41
	v_mad_u32_u24 v65, v64, s96, v62
	v_lshlrev_b32_e32 v42, 1, v75
	s_xor_b64 exec, exec, s[0:1]
	s_cbranch_execz .LBB0_844
	ds_read_b128 v[80:83], v65
	ds_read_b64_tr_b16 v[84:85], v58 offset:36864
	ds_read_b64_tr_b16 v[86:87], v58 offset:37440
	ds_read_b128 v[88:91], v65 offset:64
	ds_read_b64_tr_b16 v[92:93], v58 offset:41472
	ds_read_b64_tr_b16 v[94:95], v58 offset:42048
	s_add_u32 s8, s54, s6
	s_addc_u32 s9, s55, s7
	v_mov_b32_e32 v41, v43
	s_waitcnt lgkmcnt(3)
	v_mfma_f32_16x16x32_bf16 v[44:47], v[80:83], v[84:87], 0
	s_waitcnt lgkmcnt(0)
	v_mfma_f32_16x16x32_bf16 v[44:47], v[88:91], v[92:95], v[44:47]
	s_nop 7
	v_cvt_pk_bf16_f32 v44, v44, v45
	v_cvt_pk_bf16_f32 v45, v46, v47
	v_lshl_add_u64 v[46:47], s[8:9], 0, v[42:43]
	v_lshl_add_u64 v[46:47], v[46:47], 0, v[40:41]
.LBB0_844:
	s_or_b64 exec, exec, s[0:1]
	v_mov_b32_e32 v61, v43
	v_lshl_add_u64 v[46:47], v[46:47], 0, v[60:61]
	global_store_dwordx2 v[46:47], v[44:45], off nt
	s_and_saveexec_b64 s[0:1], vcc
	s_xor_b64 s[8:9], exec, s[0:1]
	s_cbranch_execz .LBB0_856
	v_cmp_lt_i32_e64 s[0:1], 1, v55
	s_mov_b64 s[76:77], 0
	s_mov_b64 s[84:85], 0
	s_and_saveexec_b64 s[24:25], s[0:1]
	s_xor_b64 s[80:81], exec, s[24:25]
	s_cbranch_execz .LBB0_851
	v_cmp_eq_u32_e64 s[0:1], 2, v55
	s_mov_b64 s[86:87], -1
	s_and_saveexec_b64 s[84:85], s[0:1]
	s_cbranch_execz .LBB0_848
	v_mul_u32_u24_e32 v80, 0x48, v135
	v_mad_u32_u24 v81, v64, s96, v56
	v_lshlrev_b32_e32 v82, 1, v80
	v_add_u32_e32 v80, v52, v82
	ds_read_b128 v[84:87], v81
	ds_read_b128 v[88:91], v80 offset:2304
	ds_read_b128 v[92:95], v81 offset:64
	ds_read_b128 v[96:99], v80 offset:2368
	v_add_u32_e32 v80, 0, v82
	v_add3_u32 v81, v80, v40, v74
	ds_read_b64 v[82:83], v81 offset:29952
	s_waitcnt lgkmcnt(3)
	v_mfma_f32_16x16x32_bf16 v[44:47], v[84:87], v[88:91], 0
	s_waitcnt lgkmcnt(1)
	v_mfma_f32_16x16x32_bf16 v[44:47], v[92:95], v[96:99], v[44:47]
	s_add_u32 s0, s58, s6
	s_addc_u32 s1, s59, s7
	v_mov_b32_e32 v41, v43
	s_waitcnt lgkmcnt(0)
	v_and_b32_e32 v69, 0xffff0000, v82
	v_lshlrev_b32_e32 v68, 16, v82
	s_nop 1
	v_pk_add_f32 v[44:45], v[44:45], v[68:69]
	v_and_b32_e32 v69, 0xffff0000, v83
	v_lshlrev_b32_e32 v68, 16, v83
	v_pk_add_f32 v[46:47], v[46:47], v[68:69]
	v_cvt_pk_bf16_f32 v44, v44, v45
	v_cvt_pk_bf16_f32 v45, v46, v47
	v_lshl_add_u64 v[46:47], s[0:1], 0, v[42:43]
	v_lshl_add_u64 v[46:47], v[46:47], 0, v[40:41]
	v_lshl_add_u64 v[46:47], v[46:47], 0, s[14:15]
	s_xor_b64 s[86:87], exec, -1

.LBB0_850:
	v_mad_u32_u24 v80, v64, s96, v57
	v_mad_u32_u24 v81, v135, s96, v52
	ds_read_b128 v[84:87], v80
	ds_read_b128 v[88:91], v81 offset:2304
	ds_read_b128 v[92:95], v80 offset:64
	ds_read_b128 v[96:99], v81 offset:2368
	v_add_u32_e32 v80, v53, v40
	v_mad_u32_u24 v81, v135, s96, v54
	ds_read_b64_tr_b16 v[100:101], v80 offset:55296
	ds_read_b64_tr_b16 v[102:103], v80 offset:55872
	ds_read_b128 v[104:107], v81 offset:2304
	ds_read_b64_tr_b16 v[108:109], v80 offset:59904
	ds_read_b64_tr_b16 v[110:111], v80 offset:60480
	ds_read_b128 v[112:115], v81 offset:2368
	s_waitcnt lgkmcnt(8)
	v_mfma_f32_16x16x32_bf16 v[44:47], v[84:87], v[88:91], 0
	s_add_u32 s24, s60, s6
	s_addc_u32 s25, s61, s7
	s_waitcnt lgkmcnt(6)
	v_mfma_f32_16x16x32_bf16 v[44:47], v[92:95], v[96:99], v[44:47]
	s_andn2_b64 s[76:77], s[76:77], exec
	s_waitcnt lgkmcnt(3)
	v_mfma_f32_16x16x32_bf16 v[44:47], v[100:103], v[104:107], v[44:47]
	v_mov_b32_e32 v41, v43
	s_waitcnt lgkmcnt(0)
	v_mfma_f32_16x16x32_bf16 v[44:47], v[108:111], v[112:115], v[44:47]
	s_nop 7
	v_cvt_pk_bf16_f32 v44, v44, v45
	v_cvt_pk_bf16_f32 v45, v46, v47
	v_lshl_add_u64 v[46:47], s[24:25], 0, v[42:43]
	v_lshl_add_u64 v[46:47], v[46:47], 0, v[40:41]
	v_lshl_add_u64 v[46:47], v[46:47], 0, s[14:15]
	s_or_b64 exec, exec, s[0:1]
	s_and_saveexec_b64 s[0:1], s[76:77]
	s_cbranch_execnz .LBB0_854
	s_branch .LBB0_855

.LBB0_854:
	v_add_u32_e32 v80, v49, v40
	v_mad_u32_u24 v81, v135, s96, v51
	ds_read_b64_tr_b16 v[84:85], v80 offset:36864
	ds_read_b64_tr_b16 v[86:87], v80 offset:37440
	ds_read_b128 v[88:91], v81 offset:2304
	ds_read_b64_tr_b16 v[92:93], v80 offset:41472
	ds_read_b64_tr_b16 v[94:95], v80 offset:42048
	ds_read_b128 v[96:99], v81 offset:2368
	v_lshlrev_b32_e32 v80, 3, v59
	v_lshlrev_b32_e32 v81, 1, v50
	v_add3_u32 v82, v48, v80, v81
	ds_read_b64_tr_b16 v[100:101], v82 offset:46080
	ds_read_b64_tr_b16 v[102:103], v82 offset:46656
	ds_read_b64_tr_b16 v[104:105], v49 offset:55328
	ds_read_b64_tr_b16 v[106:107], v49 offset:55904
	ds_read_b64_tr_b16 v[108:109], v82 offset:50688
	s_add_u32 s24, s56, s6
	s_addc_u32 s25, s57, s7
	s_waitcnt lgkmcnt(8)
	v_mfma_f32_16x16x32_bf16 v[44:47], v[84:87], v[88:91], 0
	ds_read_b64_tr_b16 v[110:111], v82 offset:51264
	ds_read_b64_tr_b16 v[80:81], v49 offset:59936
	ds_read_b64_tr_b16 v[82:83], v49 offset:60512
	s_waitcnt lgkmcnt(8)
	v_mfma_f32_16x16x32_bf16 v[44:47], v[92:95], v[96:99], v[44:47]
	s_waitcnt lgkmcnt(4)
	v_mfma_f32_16x16x32_bf16 v[44:47], v[100:103], v[104:107], v[44:47]
	v_mov_b32_e32 v41, v43
	s_waitcnt lgkmcnt(0)
	v_mfma_f32_16x16x32_bf16 v[44:47], v[108:111], v[80:83], v[44:47]
	s_nop 7
	v_cvt_pk_bf16_f32 v44, v44, v45
	v_cvt_pk_bf16_f32 v45, v46, v47
	v_lshl_add_u64 v[46:47], s[24:25], 0, v[42:43]
	v_lshl_add_u64 v[46:47], v[46:47], 0, v[40:41]
	v_lshl_add_u64 v[46:47], v[46:47], 0, s[14:15]

.LBB0_856:
	s_andn2_saveexec_b64 s[0:1], s[8:9]
	s_cbranch_execz .LBB0_858
	ds_read_b128 v[80:83], v65
	ds_read_b64_tr_b16 v[84:85], v58 offset:36896
	ds_read_b64_tr_b16 v[86:87], v58 offset:37472
	ds_read_b128 v[88:91], v65 offset:64
	ds_read_b64_tr_b16 v[92:93], v58 offset:41504
	ds_read_b64_tr_b16 v[94:95], v58 offset:42080
	s_add_u32 s8, s54, s6
	s_addc_u32 s9, s55, s7
	v_mov_b32_e32 v41, v43
	s_waitcnt lgkmcnt(3)
	v_mfma_f32_16x16x32_bf16 v[44:47], v[80:83], v[84:87], 0
	s_waitcnt lgkmcnt(0)
	v_mfma_f32_16x16x32_bf16 v[44:47], v[88:91], v[92:95], v[44:47]
	s_nop 7
	v_cvt_pk_bf16_f32 v44, v44, v45
	v_cvt_pk_bf16_f32 v45, v46, v47
	v_lshl_add_u64 v[46:47], s[8:9], 0, v[42:43]
	v_lshl_add_u64 v[46:47], v[46:47], 0, v[40:41]
	v_lshl_add_u64 v[46:47], v[46:47], 0, s[14:15]
.LBB0_858:
	s_or_b64 exec, exec, s[0:1]
	v_mov_b32_e32 v61, v43
	v_lshl_add_u64 v[46:47], v[46:47], 0, v[60:61]
	global_store_dwordx2 v[46:47], v[44:45], off nt
	s_and_saveexec_b64 s[0:1], vcc
	s_xor_b64 s[8:9], exec, s[0:1]
	s_cbranch_execz .LBB0_870
	v_cmp_lt_i32_e64 s[0:1], 1, v55
	s_mov_b64 s[76:77], 0
	s_mov_b64 s[84:85], 0
	s_and_saveexec_b64 s[24:25], s[0:1]
	s_xor_b64 s[80:81], exec, s[24:25]
	s_cbranch_execz .LBB0_865
	v_cmp_eq_u32_e64 s[0:1], 2, v55
	s_mov_b64 s[86:87], -1
	s_and_saveexec_b64 s[84:85], s[0:1]
	s_cbranch_execz .LBB0_862
	v_mul_u32_u24_e32 v80, 0x48, v135
	v_mad_u32_u24 v81, v64, s96, v56
	v_lshlrev_b32_e32 v82, 1, v80
	v_add_u32_e32 v80, v52, v82
	ds_read_b128 v[84:87], v81
	ds_read_b128 v[88:91], v80 offset:4608
	ds_read_b128 v[92:95], v81 offset:64
	ds_read_b128 v[96:99], v80 offset:4672
	v_add_u32_e32 v80, 0, v82
	v_add3_u32 v81, v80, v40, v74
	ds_read_b64 v[82:83], v81 offset:32256
	s_waitcnt lgkmcnt(3)
	v_mfma_f32_16x16x32_bf16 v[44:47], v[84:87], v[88:91], 0
	s_waitcnt lgkmcnt(1)
	v_mfma_f32_16x16x32_bf16 v[44:47], v[92:95], v[96:99], v[44:47]
	s_add_u32 s0, s58, s6
	s_addc_u32 s1, s59, s7
	v_mov_b32_e32 v41, v43
	s_waitcnt lgkmcnt(0)
	v_and_b32_e32 v69, 0xffff0000, v82
	v_lshlrev_b32_e32 v68, 16, v82
	s_nop 1
	v_pk_add_f32 v[44:45], v[44:45], v[68:69]
	v_and_b32_e32 v69, 0xffff0000, v83
	v_lshlrev_b32_e32 v68, 16, v83
	v_pk_add_f32 v[46:47], v[46:47], v[68:69]
	v_cvt_pk_bf16_f32 v44, v44, v45
	v_cvt_pk_bf16_f32 v45, v46, v47
	v_lshl_add_u64 v[46:47], s[0:1], 0, v[42:43]
	v_lshl_add_u64 v[46:47], v[46:47], 0, v[40:41]
	v_lshl_add_u64 v[46:47], v[46:47], 0, s[72:73]
	s_xor_b64 s[86:87], exec, -1

.LBB0_864:
	v_mad_u32_u24 v80, v64, s96, v57
	v_mad_u32_u24 v81, v135, s96, v52
	ds_read_b128 v[84:87], v80
	ds_read_b128 v[88:91], v81 offset:4608
	ds_read_b128 v[92:95], v80 offset:64
	ds_read_b128 v[96:99], v81 offset:4672
	v_add_u32_e32 v80, v53, v40
	v_mad_u32_u24 v81, v135, s96, v54
	ds_read_b64_tr_b16 v[100:101], v80 offset:55296
	ds_read_b64_tr_b16 v[102:103], v80 offset:55872
	ds_read_b128 v[104:107], v81 offset:4608
	ds_read_b64_tr_b16 v[108:109], v80 offset:59904
	ds_read_b64_tr_b16 v[110:111], v80 offset:60480
	ds_read_b128 v[112:115], v81 offset:4672
	s_waitcnt lgkmcnt(8)
	v_mfma_f32_16x16x32_bf16 v[44:47], v[84:87], v[88:91], 0
	s_add_u32 s24, s60, s6
	s_addc_u32 s25, s61, s7
	s_waitcnt lgkmcnt(6)
	v_mfma_f32_16x16x32_bf16 v[44:47], v[92:95], v[96:99], v[44:47]
	s_andn2_b64 s[76:77], s[76:77], exec
	s_waitcnt lgkmcnt(3)
	v_mfma_f32_16x16x32_bf16 v[44:47], v[100:103], v[104:107], v[44:47]
	v_mov_b32_e32 v41, v43
	s_waitcnt lgkmcnt(0)
	v_mfma_f32_16x16x32_bf16 v[44:47], v[108:111], v[112:115], v[44:47]
	s_nop 7
	v_cvt_pk_bf16_f32 v44, v44, v45
	v_cvt_pk_bf16_f32 v45, v46, v47
	v_lshl_add_u64 v[46:47], s[24:25], 0, v[42:43]
	v_lshl_add_u64 v[46:47], v[46:47], 0, v[40:41]
	v_lshl_add_u64 v[46:47], v[46:47], 0, s[72:73]
	s_or_b64 exec, exec, s[0:1]
	s_and_saveexec_b64 s[0:1], s[76:77]
	s_cbranch_execnz .LBB0_868
	s_branch .LBB0_869

.LBB0_868:
	v_add_u32_e32 v80, v49, v40
	v_mad_u32_u24 v81, v135, s96, v51
	ds_read_b64_tr_b16 v[84:85], v80 offset:36864
	ds_read_b64_tr_b16 v[86:87], v80 offset:37440
	ds_read_b128 v[88:91], v81 offset:4608
	ds_read_b64_tr_b16 v[92:93], v80 offset:41472
	ds_read_b64_tr_b16 v[94:95], v80 offset:42048
	ds_read_b128 v[96:99], v81 offset:4672
	v_lshlrev_b32_e32 v80, 3, v59
	v_lshlrev_b32_e32 v81, 1, v50
	v_add3_u32 v82, v48, v80, v81
	ds_read_b64_tr_b16 v[100:101], v82 offset:46080
	ds_read_b64_tr_b16 v[102:103], v82 offset:46656
	ds_read_b64_tr_b16 v[104:105], v49 offset:55360
	ds_read_b64_tr_b16 v[106:107], v49 offset:55936
	ds_read_b64_tr_b16 v[108:109], v82 offset:50688
	s_add_u32 s24, s56, s6
	s_addc_u32 s25, s57, s7
	s_waitcnt lgkmcnt(8)
	v_mfma_f32_16x16x32_bf16 v[44:47], v[84:87], v[88:91], 0
	ds_read_b64_tr_b16 v[110:111], v82 offset:51264
	ds_read_b64_tr_b16 v[80:81], v49 offset:59968
	ds_read_b64_tr_b16 v[82:83], v49 offset:60544
	s_waitcnt lgkmcnt(8)
	v_mfma_f32_16x16x32_bf16 v[44:47], v[92:95], v[96:99], v[44:47]
	s_waitcnt lgkmcnt(4)
	v_mfma_f32_16x16x32_bf16 v[44:47], v[100:103], v[104:107], v[44:47]
	v_mov_b32_e32 v41, v43
	s_waitcnt lgkmcnt(0)
	v_mfma_f32_16x16x32_bf16 v[44:47], v[108:111], v[80:83], v[44:47]
	s_nop 7
	v_cvt_pk_bf16_f32 v44, v44, v45
	v_cvt_pk_bf16_f32 v45, v46, v47
	v_lshl_add_u64 v[46:47], s[24:25], 0, v[42:43]
	v_lshl_add_u64 v[46:47], v[46:47], 0, v[40:41]
	v_lshl_add_u64 v[46:47], v[46:47], 0, s[72:73]

.LBB0_870:
	s_andn2_saveexec_b64 s[0:1], s[8:9]
	s_cbranch_execz .LBB0_872
	ds_read_b128 v[80:83], v65
	ds_read_b64_tr_b16 v[84:85], v58 offset:36928
	ds_read_b64_tr_b16 v[86:87], v58 offset:37504
	ds_read_b128 v[88:91], v65 offset:64
	ds_read_b64_tr_b16 v[92:93], v58 offset:41536
	ds_read_b64_tr_b16 v[94:95], v58 offset:42112
	s_add_u32 s8, s54, s6
	s_addc_u32 s9, s55, s7
	v_mov_b32_e32 v41, v43
	s_waitcnt lgkmcnt(3)
	v_mfma_f32_16x16x32_bf16 v[44:47], v[80:83], v[84:87], 0
	s_waitcnt lgkmcnt(0)
	v_mfma_f32_16x16x32_bf16 v[44:47], v[88:91], v[92:95], v[44:47]
	s_nop 7
	v_cvt_pk_bf16_f32 v44, v44, v45
	v_cvt_pk_bf16_f32 v45, v46, v47
	v_lshl_add_u64 v[46:47], s[8:9], 0, v[42:43]
	v_lshl_add_u64 v[46:47], v[46:47], 0, v[40:41]
	v_lshl_add_u64 v[46:47], v[46:47], 0, s[72:73]
.LBB0_872:
	s_or_b64 exec, exec, s[0:1]
	v_mov_b32_e32 v61, v43
	v_lshl_add_u64 v[46:47], v[46:47], 0, v[60:61]
	global_store_dwordx2 v[46:47], v[44:45], off nt
	s_and_saveexec_b64 s[0:1], vcc
	s_xor_b64 s[8:9], exec, s[0:1]
	s_cbranch_execz .LBB0_884
	v_cmp_lt_i32_e64 s[0:1], 1, v55
	s_mov_b64 s[76:77], 0
	s_mov_b64 s[84:85], 0
	s_and_saveexec_b64 s[24:25], s[0:1]
	s_xor_b64 s[80:81], exec, s[24:25]
	s_cbranch_execz .LBB0_879
	v_cmp_eq_u32_e64 s[0:1], 2, v55
	s_mov_b64 s[86:87], -1
	s_and_saveexec_b64 s[84:85], s[0:1]
	s_cbranch_execz .LBB0_876
	v_mul_u32_u24_e32 v44, 0x48, v135
	v_mad_u32_u24 v80, v64, s96, v56
	ds_read_b128 v[84:87], v80
	v_lshlrev_b32_e32 v61, 1, v44
	v_add_u32_e32 v65, v52, v61
	ds_read_b128 v[88:91], v65 offset:6912
	ds_read_b128 v[92:95], v80 offset:64
	ds_read_b128 v[80:83], v65 offset:6976
	v_add_u32_e32 v96, 0, v61
	v_add3_u32 v97, v96, v40, v74
	ds_read_b64 v[98:99], v97 offset:34560
	s_waitcnt lgkmcnt(3)
	v_mfma_f32_16x16x32_bf16 v[44:47], v[84:87], v[88:91], 0
	s_waitcnt lgkmcnt(1)
	v_mfma_f32_16x16x32_bf16 v[44:47], v[92:95], v[80:83], v[44:47]
	s_add_u32 s0, s58, s6
	s_addc_u32 s1, s59, s7
	v_mov_b32_e32 v41, v43
	s_waitcnt lgkmcnt(0)
	v_and_b32_e32 v69, 0xffff0000, v98
	v_lshlrev_b32_e32 v68, 16, v98
	s_nop 1
	v_pk_add_f32 v[44:45], v[44:45], v[68:69]
	v_and_b32_e32 v69, 0xffff0000, v99
	v_lshlrev_b32_e32 v68, 16, v99
	v_pk_add_f32 v[46:47], v[46:47], v[68:69]
	v_cvt_pk_bf16_f32 v44, v44, v45
	v_cvt_pk_bf16_f32 v45, v46, v47
	v_lshl_add_u64 v[46:47], s[0:1], 0, v[42:43]
	v_lshl_add_u64 v[46:47], v[46:47], 0, v[40:41]
	v_lshl_add_u64 v[46:47], v[46:47], 0, s[74:75]
	s_xor_b64 s[86:87], exec, -1

.LBB0_878:
	v_mad_u32_u24 v80, v64, s96, v57
	v_mad_u32_u24 v81, v135, s96, v52
	ds_read_b128 v[84:87], v80
	ds_read_b128 v[88:91], v81 offset:6912
	ds_read_b128 v[92:95], v80 offset:64
	ds_read_b128 v[96:99], v81 offset:6976
	v_add_u32_e32 v61, v53, v40
	v_mad_u32_u24 v80, v135, s96, v54
	ds_read_b64_tr_b16 v[100:101], v61 offset:55296
	ds_read_b64_tr_b16 v[102:103], v61 offset:55872
	ds_read_b128 v[104:107], v80 offset:6912
	ds_read_b128 v[108:111], v80 offset:6976
	s_waitcnt lgkmcnt(6)
	v_mfma_f32_16x16x32_bf16 v[44:47], v[84:87], v[88:91], 0
	s_add_u32 s24, s60, s6
	s_addc_u32 s25, s61, s7
	s_waitcnt lgkmcnt(4)
	v_mfma_f32_16x16x32_bf16 v[44:47], v[92:95], v[96:99], v[44:47]
	s_andn2_b64 s[76:77], s[76:77], exec
	s_waitcnt lgkmcnt(1)
	v_mfma_f32_16x16x32_bf16 v[44:47], v[100:103], v[104:107], v[44:47]
	ds_read_b64_tr_b16 v[64:65], v61 offset:59904
	ds_read_b64_tr_b16 v[66:67], v61 offset:60480
	v_mov_b32_e32 v41, v43
	s_waitcnt lgkmcnt(0)
	v_mfma_f32_16x16x32_bf16 v[44:47], v[64:67], v[108:111], v[44:47]
	s_nop 7
	v_cvt_pk_bf16_f32 v44, v44, v45
	v_cvt_pk_bf16_f32 v45, v46, v47
	v_lshl_add_u64 v[46:47], s[24:25], 0, v[42:43]
	v_lshl_add_u64 v[46:47], v[46:47], 0, v[40:41]
	v_lshl_add_u64 v[46:47], v[46:47], 0, s[74:75]
	s_or_b64 exec, exec, s[0:1]
	s_and_saveexec_b64 s[0:1], s[76:77]
	s_cbranch_execnz .LBB0_882
	s_branch .LBB0_883

.LBB0_882:
	v_add_u32_e32 v80, v49, v40
	v_mad_u32_u24 v81, v135, s96, v51
	ds_read_b64_tr_b16 v[84:85], v80 offset:36864
	ds_read_b64_tr_b16 v[86:87], v80 offset:37440
	ds_read_b128 v[88:91], v81 offset:6912
	ds_read_b64_tr_b16 v[92:93], v80 offset:41472
	ds_read_b64_tr_b16 v[94:95], v80 offset:42048
	ds_read_b128 v[96:99], v81 offset:6976
	s_add_u32 s24, s56, s6
	s_addc_u32 s25, s57, s7
	s_waitcnt lgkmcnt(3)
	v_mfma_f32_16x16x32_bf16 v[44:47], v[84:87], v[88:91], 0
	v_lshlrev_b32_e32 v41, 3, v59
	v_lshlrev_b32_e32 v61, 1, v50
	v_add3_u32 v41, v48, v41, v61
	ds_read_b64_tr_b16 v[80:81], v41 offset:46080
	ds_read_b64_tr_b16 v[82:83], v41 offset:46656
	s_waitcnt lgkmcnt(2)
	v_mfma_f32_16x16x32_bf16 v[44:47], v[92:95], v[96:99], v[44:47]
	ds_read_b64_tr_b16 v[84:85], v49 offset:55392
	ds_read_b64_tr_b16 v[86:87], v49 offset:55968
	ds_read_b64_tr_b16 v[88:89], v49 offset:60000
	ds_read_b64_tr_b16 v[90:91], v49 offset:60576
	s_waitcnt lgkmcnt(2)
	v_mfma_f32_16x16x32_bf16 v[44:47], v[80:83], v[84:87], v[44:47]
	ds_read_b64_tr_b16 v[64:65], v41 offset:50688
	ds_read_b64_tr_b16 v[66:67], v41 offset:51264
	v_mov_b32_e32 v41, v43
	s_waitcnt lgkmcnt(0)
	v_mfma_f32_16x16x32_bf16 v[44:47], v[64:67], v[88:91], v[44:47]
	s_nop 7
	v_cvt_pk_bf16_f32 v44, v44, v45
	v_cvt_pk_bf16_f32 v45, v46, v47
	v_lshl_add_u64 v[46:47], s[24:25], 0, v[42:43]
	v_lshl_add_u64 v[40:41], v[46:47], 0, v[40:41]
	v_lshl_add_u64 v[46:47], v[40:41], 0, s[74:75]

.LBB0_884:
	s_andn2_saveexec_b64 s[0:1], s[8:9]
	s_cbranch_execz .LBB0_886
	ds_read_b128 v[80:83], v65
	ds_read_b64_tr_b16 v[84:85], v58 offset:36960
	ds_read_b64_tr_b16 v[86:87], v58 offset:37536
	ds_read_b128 v[88:91], v65 offset:64
	ds_read_b64_tr_b16 v[92:93], v58 offset:41568
	ds_read_b64_tr_b16 v[94:95], v58 offset:42144
	s_add_u32 s8, s54, s6
	s_addc_u32 s9, s55, s7
	v_mov_b32_e32 v41, v43
	s_waitcnt lgkmcnt(3)
	v_mfma_f32_16x16x32_bf16 v[44:47], v[80:83], v[84:87], 0
	s_waitcnt lgkmcnt(0)
	v_mfma_f32_16x16x32_bf16 v[44:47], v[88:91], v[92:95], v[44:47]
	s_nop 7
	v_cvt_pk_bf16_f32 v44, v44, v45
	v_cvt_pk_bf16_f32 v45, v46, v47
	v_lshl_add_u64 v[46:47], s[8:9], 0, v[42:43]
	v_lshl_add_u64 v[40:41], v[46:47], 0, v[40:41]
	v_lshl_add_u64 v[46:47], v[40:41], 0, s[74:75]
.LBB0_886:
	s_or_b64 exec, exec, s[0:1]
	v_mov_b32_e32 v61, v43
	v_lshl_add_u64 v[40:41], v[46:47], 0, v[60:61]
	global_store_dwordx2 v[40:41], v[44:45], off nt
	v_lshrrev_b32_e32 v40, 2, v59
	v_or_b32_e32 v59, 1, v40
	v_lshlrev_b32_e32 v40, 4, v59
	s_and_saveexec_b64 s[0:1], vcc
	s_xor_b64 s[8:9], exec, s[0:1]
	s_cbranch_execz .LBB0_898
	v_cmp_lt_i32_e64 s[0:1], 1, v55
	s_mov_b64 s[76:77], 0
	s_mov_b64 s[84:85], 0
	s_and_saveexec_b64 s[24:25], s[0:1]
	s_xor_b64 s[80:81], exec, s[24:25]
	s_cbranch_execz .LBB0_893
	v_cmp_eq_u32_e64 s[0:1], 2, v55
	s_mov_b64 s[86:87], -1
	s_and_saveexec_b64 s[84:85], s[0:1]
	s_cbranch_execz .LBB0_890
	v_or_b32_e32 v80, v40, v135
	v_mul_u32_u24_e32 v81, 0x48, v135
	v_mad_u32_u24 v82, v80, s96, v56
	v_lshlrev_b32_e32 v80, 1, v81
	v_add_u32_e32 v81, v52, v80
	ds_read_b128 v[84:87], v82
	ds_read_b128 v[88:91], v81
	ds_read_b128 v[92:95], v82 offset:64
	ds_read_b128 v[96:99], v81 offset:64
	s_waitcnt lgkmcnt(2)
	v_mfma_f32_16x16x32_bf16 v[44:47], v[84:87], v[88:91], 0
	v_lshlrev_b32_e32 v64, 1, v40
	v_add_u32_e32 v81, 0, v80
	v_add3_u32 v80, v81, v64, v74
	ds_read_b64 v[82:83], v80 offset:27648
	s_waitcnt lgkmcnt(1)
	v_mfma_f32_16x16x32_bf16 v[44:47], v[92:95], v[96:99], v[44:47]
	s_add_u32 s0, s58, s6
	s_addc_u32 s1, s59, s7
	v_mov_b32_e32 v65, v43
	s_waitcnt lgkmcnt(0)
	v_and_b32_e32 v69, 0xffff0000, v82
	v_lshlrev_b32_e32 v68, 16, v82
	s_nop 1
	v_pk_add_f32 v[44:45], v[44:45], v[68:69]
	v_and_b32_e32 v69, 0xffff0000, v83
	v_lshlrev_b32_e32 v68, 16, v83
	v_pk_add_f32 v[46:47], v[46:47], v[68:69]
	v_cvt_pk_bf16_f32 v44, v44, v45
	v_cvt_pk_bf16_f32 v45, v46, v47
	v_lshl_add_u64 v[46:47], s[0:1], 0, v[42:43]
	v_lshl_add_u64 v[46:47], v[46:47], 0, v[64:65]
	s_xor_b64 s[86:87], exec, -1

.LBB0_892:
	v_or_b32_e32 v80, v40, v135
	v_mad_u32_u24 v81, v80, s96, v57
	v_add_u32_e32 v80, v52, v63
	ds_read_b128 v[84:87], v81
	ds_read_b128 v[88:91], v80
	ds_read_b128 v[92:95], v81 offset:64
	ds_read_b128 v[96:99], v80 offset:64
	v_lshlrev_b32_e32 v72, 1, v40
	v_add_u32_e32 v80, v53, v72
	v_add_u32_e32 v81, v54, v63
	ds_read_b64_tr_b16 v[100:101], v80 offset:55296
	ds_read_b64_tr_b16 v[102:103], v80 offset:55872
	ds_read_b128 v[104:107], v81
	ds_read_b64_tr_b16 v[108:109], v80 offset:59904
	s_waitcnt lgkmcnt(6)
	v_mfma_f32_16x16x32_bf16 v[44:47], v[84:87], v[88:91], 0
	s_add_u32 s24, s60, s6
	s_waitcnt lgkmcnt(4)
	v_mfma_f32_16x16x32_bf16 v[44:47], v[92:95], v[96:99], v[44:47]
	ds_read_b64_tr_b16 v[110:111], v80 offset:60480
	ds_read_b128 v[84:87], v81 offset:64
	s_addc_u32 s25, s61, s7
	v_mov_b32_e32 v73, v43
	s_waitcnt lgkmcnt(3)
	v_mfma_f32_16x16x32_bf16 v[44:47], v[100:103], v[104:107], v[44:47]
	s_andn2_b64 s[76:77], s[76:77], exec
	s_waitcnt lgkmcnt(0)
	v_mfma_f32_16x16x32_bf16 v[44:47], v[108:111], v[84:87], v[44:47]
	s_nop 7
	v_cvt_pk_bf16_f32 v44, v44, v45
	v_cvt_pk_bf16_f32 v45, v46, v47
	v_lshl_add_u64 v[46:47], s[24:25], 0, v[42:43]
	v_lshl_add_u64 v[46:47], v[46:47], 0, v[72:73]
	s_or_b64 exec, exec, s[0:1]
	s_and_saveexec_b64 s[0:1], s[76:77]
	s_cbranch_execnz .LBB0_896
	s_branch .LBB0_897

.LBB0_896:
	v_lshlrev_b32_e32 v72, 1, v40
	v_add_u32_e32 v80, v49, v72
	v_add_u32_e32 v81, v51, v63
	ds_read_b64_tr_b16 v[84:85], v80 offset:36864
	ds_read_b64_tr_b16 v[86:87], v80 offset:37440
	ds_read_b128 v[88:91], v81
	ds_read_b64_tr_b16 v[92:93], v80 offset:41472
	ds_read_b64_tr_b16 v[94:95], v80 offset:42048
	ds_read_b128 v[96:99], v81 offset:64
	v_lshlrev_b32_e32 v80, 5, v59
	v_lshlrev_b32_e32 v81, 1, v50
	v_add3_u32 v82, v48, v80, v81
	ds_read_b64_tr_b16 v[100:101], v82 offset:46080
	ds_read_b64_tr_b16 v[102:103], v82 offset:46656
	ds_read_b64_tr_b16 v[104:105], v49 offset:55296
	ds_read_b64_tr_b16 v[106:107], v49 offset:55872
	ds_read_b64_tr_b16 v[108:109], v82 offset:50688
	s_add_u32 s24, s56, s6
	s_addc_u32 s25, s57, s7
	v_mov_b32_e32 v73, v43
	s_waitcnt lgkmcnt(8)
	v_mfma_f32_16x16x32_bf16 v[44:47], v[84:87], v[88:91], 0
	ds_read_b64_tr_b16 v[110:111], v82 offset:51264
	ds_read_b64_tr_b16 v[80:81], v49 offset:59904
	ds_read_b64_tr_b16 v[82:83], v49 offset:60480
	s_waitcnt lgkmcnt(8)
	v_mfma_f32_16x16x32_bf16 v[44:47], v[92:95], v[96:99], v[44:47]
	s_waitcnt lgkmcnt(4)
	v_mfma_f32_16x16x32_bf16 v[44:47], v[100:103], v[104:107], v[44:47]
	s_waitcnt lgkmcnt(0)
	v_mfma_f32_16x16x32_bf16 v[44:47], v[108:111], v[80:83], v[44:47]
	s_nop 7
	v_cvt_pk_bf16_f32 v44, v44, v45
	v_cvt_pk_bf16_f32 v45, v46, v47
	v_lshl_add_u64 v[46:47], s[24:25], 0, v[42:43]
	v_lshl_add_u64 v[46:47], v[46:47], 0, v[72:73]

.LBB0_898:
	s_or_saveexec_b64 s[0:1], s[8:9]
	v_or_b32_e32 v63, v40, v135
	v_lshlrev_b32_e32 v40, 1, v40
	v_mad_u32_u24 v62, v63, s96, v62
	s_xor_b64 exec, exec, s[0:1]
	s_cbranch_execz .LBB0_900
	ds_read_b128 v[80:83], v62
	ds_read_b64_tr_b16 v[84:85], v58 offset:36864
	ds_read_b64_tr_b16 v[86:87], v58 offset:37440
	ds_read_b128 v[88:91], v62 offset:64
	ds_read_b64_tr_b16 v[92:93], v58 offset:41472
	ds_read_b64_tr_b16 v[94:95], v58 offset:42048
	s_add_u32 s8, s54, s6
	s_addc_u32 s9, s55, s7
	v_mov_b32_e32 v41, v43
	s_waitcnt lgkmcnt(3)
	v_mfma_f32_16x16x32_bf16 v[44:47], v[80:83], v[84:87], 0
	s_waitcnt lgkmcnt(0)
	v_mfma_f32_16x16x32_bf16 v[44:47], v[88:91], v[92:95], v[44:47]
	s_nop 7
	v_cvt_pk_bf16_f32 v44, v44, v45
	v_cvt_pk_bf16_f32 v45, v46, v47
	v_lshl_add_u64 v[46:47], s[8:9], 0, v[42:43]
	v_lshl_add_u64 v[46:47], v[46:47], 0, v[40:41]
.LBB0_900:
	s_or_b64 exec, exec, s[0:1]
	v_mov_b32_e32 v61, v43
	v_lshl_add_u64 v[46:47], v[46:47], 0, v[60:61]
	global_store_dwordx2 v[46:47], v[44:45], off nt
	s_and_saveexec_b64 s[0:1], vcc
	s_xor_b64 s[8:9], exec, s[0:1]
	s_cbranch_execz .LBB0_912
	v_cmp_lt_i32_e64 s[0:1], 1, v55
	s_mov_b64 s[76:77], 0
	s_mov_b64 s[84:85], 0
	s_and_saveexec_b64 s[24:25], s[0:1]
	s_xor_b64 s[80:81], exec, s[24:25]
	s_cbranch_execz .LBB0_907
	v_cmp_eq_u32_e64 s[0:1], 2, v55
	s_mov_b64 s[86:87], -1
	s_and_saveexec_b64 s[84:85], s[0:1]
	s_cbranch_execz .LBB0_904
	v_mul_u32_u24_e32 v80, 0x48, v135
	v_mad_u32_u24 v81, v63, s96, v56
	v_lshlrev_b32_e32 v82, 1, v80
	v_add_u32_e32 v80, v52, v82
	ds_read_b128 v[84:87], v81
	ds_read_b128 v[88:91], v80 offset:2304
	ds_read_b128 v[92:95], v81 offset:64
	ds_read_b128 v[96:99], v80 offset:2368
	v_add_u32_e32 v80, 0, v82
	v_add3_u32 v81, v80, v40, v74
	ds_read_b64 v[82:83], v81 offset:29952
	s_waitcnt lgkmcnt(3)
	v_mfma_f32_16x16x32_bf16 v[44:47], v[84:87], v[88:91], 0
	s_waitcnt lgkmcnt(1)
	v_mfma_f32_16x16x32_bf16 v[44:47], v[92:95], v[96:99], v[44:47]
	s_add_u32 s0, s58, s6
	s_addc_u32 s1, s59, s7
	v_mov_b32_e32 v41, v43
	s_waitcnt lgkmcnt(0)
	v_and_b32_e32 v67, 0xffff0000, v82
	v_lshlrev_b32_e32 v66, 16, v82
	s_nop 1
	v_pk_add_f32 v[44:45], v[44:45], v[66:67]
	v_and_b32_e32 v67, 0xffff0000, v83
	v_lshlrev_b32_e32 v66, 16, v83
	v_pk_add_f32 v[46:47], v[46:47], v[66:67]
	v_cvt_pk_bf16_f32 v44, v44, v45
	v_cvt_pk_bf16_f32 v45, v46, v47
	v_lshl_add_u64 v[46:47], s[0:1], 0, v[42:43]
	v_lshl_add_u64 v[46:47], v[46:47], 0, v[40:41]
	v_lshl_add_u64 v[46:47], v[46:47], 0, s[14:15]
	s_xor_b64 s[86:87], exec, -1

.LBB0_906:
	v_mad_u32_u24 v80, v63, s96, v57
	v_mad_u32_u24 v81, v135, s96, v52
	ds_read_b128 v[84:87], v80
	ds_read_b128 v[88:91], v81 offset:2304
	ds_read_b128 v[92:95], v80 offset:64
	ds_read_b128 v[96:99], v81 offset:2368
	v_add_u32_e32 v80, v53, v40
	v_mad_u32_u24 v81, v135, s96, v54
	ds_read_b64_tr_b16 v[100:101], v80 offset:55296
	ds_read_b64_tr_b16 v[102:103], v80 offset:55872
	ds_read_b128 v[104:107], v81 offset:2304
	ds_read_b64_tr_b16 v[108:109], v80 offset:59904
	ds_read_b64_tr_b16 v[110:111], v80 offset:60480
	ds_read_b128 v[112:115], v81 offset:2368
	s_waitcnt lgkmcnt(8)
	v_mfma_f32_16x16x32_bf16 v[44:47], v[84:87], v[88:91], 0
	s_add_u32 s24, s60, s6
	s_addc_u32 s25, s61, s7
	s_waitcnt lgkmcnt(6)
	v_mfma_f32_16x16x32_bf16 v[44:47], v[92:95], v[96:99], v[44:47]
	s_andn2_b64 s[76:77], s[76:77], exec
	s_waitcnt lgkmcnt(3)
	v_mfma_f32_16x16x32_bf16 v[44:47], v[100:103], v[104:107], v[44:47]
	v_mov_b32_e32 v41, v43
	s_waitcnt lgkmcnt(0)
	v_mfma_f32_16x16x32_bf16 v[44:47], v[108:111], v[112:115], v[44:47]
	s_nop 7
	v_cvt_pk_bf16_f32 v44, v44, v45
	v_cvt_pk_bf16_f32 v45, v46, v47
	v_lshl_add_u64 v[46:47], s[24:25], 0, v[42:43]
	v_lshl_add_u64 v[46:47], v[46:47], 0, v[40:41]
	v_lshl_add_u64 v[46:47], v[46:47], 0, s[14:15]
	s_or_b64 exec, exec, s[0:1]
	s_and_saveexec_b64 s[0:1], s[76:77]
	s_cbranch_execnz .LBB0_910
	s_branch .LBB0_911

.LBB0_910:
	v_add_u32_e32 v80, v49, v40
	v_mad_u32_u24 v81, v135, s96, v51
	ds_read_b64_tr_b16 v[84:85], v80 offset:36864
	ds_read_b64_tr_b16 v[86:87], v80 offset:37440
	ds_read_b128 v[88:91], v81 offset:2304
	ds_read_b64_tr_b16 v[92:93], v80 offset:41472
	ds_read_b64_tr_b16 v[94:95], v80 offset:42048
	ds_read_b128 v[96:99], v81 offset:2368
	v_lshlrev_b32_e32 v80, 5, v59
	v_lshlrev_b32_e32 v81, 1, v50
	v_add3_u32 v82, v48, v80, v81
	ds_read_b64_tr_b16 v[100:101], v82 offset:46080
	ds_read_b64_tr_b16 v[102:103], v82 offset:46656
	ds_read_b64_tr_b16 v[104:105], v49 offset:55328
	ds_read_b64_tr_b16 v[106:107], v49 offset:55904
	ds_read_b64_tr_b16 v[108:109], v82 offset:50688
	s_add_u32 s24, s56, s6
	s_addc_u32 s25, s57, s7
	s_waitcnt lgkmcnt(8)
	v_mfma_f32_16x16x32_bf16 v[44:47], v[84:87], v[88:91], 0
	ds_read_b64_tr_b16 v[110:111], v82 offset:51264
	ds_read_b64_tr_b16 v[80:81], v49 offset:59936
	ds_read_b64_tr_b16 v[82:83], v49 offset:60512
	s_waitcnt lgkmcnt(8)
	v_mfma_f32_16x16x32_bf16 v[44:47], v[92:95], v[96:99], v[44:47]
	s_waitcnt lgkmcnt(4)
	v_mfma_f32_16x16x32_bf16 v[44:47], v[100:103], v[104:107], v[44:47]
	v_mov_b32_e32 v41, v43
	s_waitcnt lgkmcnt(0)
	v_mfma_f32_16x16x32_bf16 v[44:47], v[108:111], v[80:83], v[44:47]
	s_nop 7
	v_cvt_pk_bf16_f32 v44, v44, v45
	v_cvt_pk_bf16_f32 v45, v46, v47
	v_lshl_add_u64 v[46:47], s[24:25], 0, v[42:43]
	v_lshl_add_u64 v[46:47], v[46:47], 0, v[40:41]
	v_lshl_add_u64 v[46:47], v[46:47], 0, s[14:15]

.LBB0_912:
	s_andn2_saveexec_b64 s[0:1], s[8:9]
	s_cbranch_execz .LBB0_914
	ds_read_b128 v[80:83], v62
	ds_read_b64_tr_b16 v[84:85], v58 offset:36896
	ds_read_b64_tr_b16 v[86:87], v58 offset:37472
	ds_read_b128 v[88:91], v62 offset:64
	ds_read_b64_tr_b16 v[92:93], v58 offset:41504
	ds_read_b64_tr_b16 v[94:95], v58 offset:42080
	s_add_u32 s8, s54, s6
	s_addc_u32 s9, s55, s7
	v_mov_b32_e32 v41, v43
	s_waitcnt lgkmcnt(3)
	v_mfma_f32_16x16x32_bf16 v[44:47], v[80:83], v[84:87], 0
	s_waitcnt lgkmcnt(0)
	v_mfma_f32_16x16x32_bf16 v[44:47], v[88:91], v[92:95], v[44:47]
	s_nop 7
	v_cvt_pk_bf16_f32 v44, v44, v45
	v_cvt_pk_bf16_f32 v45, v46, v47
	v_lshl_add_u64 v[46:47], s[8:9], 0, v[42:43]
	v_lshl_add_u64 v[46:47], v[46:47], 0, v[40:41]
	v_lshl_add_u64 v[46:47], v[46:47], 0, s[14:15]
.LBB0_914:
	s_or_b64 exec, exec, s[0:1]
	v_mov_b32_e32 v61, v43
	v_lshl_add_u64 v[46:47], v[46:47], 0, v[60:61]
	global_store_dwordx2 v[46:47], v[44:45], off nt
	s_and_saveexec_b64 s[0:1], vcc
	s_xor_b64 s[8:9], exec, s[0:1]
	s_cbranch_execz .LBB0_926
	v_cmp_lt_i32_e64 s[0:1], 1, v55
	s_mov_b64 s[76:77], 0
	s_mov_b64 s[84:85], 0
	s_and_saveexec_b64 s[24:25], s[0:1]
	s_xor_b64 s[80:81], exec, s[24:25]
	s_cbranch_execz .LBB0_921
	v_cmp_eq_u32_e64 s[0:1], 2, v55
	s_mov_b64 s[86:87], -1
	s_and_saveexec_b64 s[84:85], s[0:1]
	s_cbranch_execz .LBB0_918
	v_mul_u32_u24_e32 v80, 0x48, v135
	v_mad_u32_u24 v81, v63, s96, v56
	v_lshlrev_b32_e32 v82, 1, v80
	v_add_u32_e32 v80, v52, v82
	ds_read_b128 v[84:87], v81
	ds_read_b128 v[88:91], v80 offset:4608
	ds_read_b128 v[92:95], v81 offset:64
	ds_read_b128 v[96:99], v80 offset:4672
	v_add_u32_e32 v80, 0, v82
	v_add3_u32 v81, v80, v40, v74
	ds_read_b64 v[82:83], v81 offset:32256
	s_waitcnt lgkmcnt(3)
	v_mfma_f32_16x16x32_bf16 v[44:47], v[84:87], v[88:91], 0
	s_waitcnt lgkmcnt(1)
	v_mfma_f32_16x16x32_bf16 v[44:47], v[92:95], v[96:99], v[44:47]
	s_add_u32 s0, s58, s6
	s_addc_u32 s1, s59, s7
	v_mov_b32_e32 v41, v43
	s_waitcnt lgkmcnt(0)
	v_and_b32_e32 v67, 0xffff0000, v82
	v_lshlrev_b32_e32 v66, 16, v82
	s_nop 1
	v_pk_add_f32 v[44:45], v[44:45], v[66:67]
	v_and_b32_e32 v67, 0xffff0000, v83
	v_lshlrev_b32_e32 v66, 16, v83
	v_pk_add_f32 v[46:47], v[46:47], v[66:67]
	v_cvt_pk_bf16_f32 v44, v44, v45
	v_cvt_pk_bf16_f32 v45, v46, v47
	v_lshl_add_u64 v[46:47], s[0:1], 0, v[42:43]
	v_lshl_add_u64 v[46:47], v[46:47], 0, v[40:41]
	v_lshl_add_u64 v[46:47], v[46:47], 0, s[72:73]
	s_xor_b64 s[86:87], exec, -1

.LBB0_920:
	v_mad_u32_u24 v80, v63, s96, v57
	v_mad_u32_u24 v81, v135, s96, v52
	ds_read_b128 v[84:87], v80
	ds_read_b128 v[88:91], v81 offset:4608
	ds_read_b128 v[92:95], v80 offset:64
	ds_read_b128 v[96:99], v81 offset:4672
	v_add_u32_e32 v80, v53, v40
	v_mad_u32_u24 v81, v135, s96, v54
	ds_read_b64_tr_b16 v[100:101], v80 offset:55296
	ds_read_b64_tr_b16 v[102:103], v80 offset:55872
	ds_read_b128 v[104:107], v81 offset:4608
	ds_read_b64_tr_b16 v[108:109], v80 offset:59904
	ds_read_b64_tr_b16 v[110:111], v80 offset:60480
	ds_read_b128 v[112:115], v81 offset:4672
	s_waitcnt lgkmcnt(8)
	v_mfma_f32_16x16x32_bf16 v[44:47], v[84:87], v[88:91], 0
	s_add_u32 s24, s60, s6
	s_addc_u32 s25, s61, s7
	s_waitcnt lgkmcnt(6)
	v_mfma_f32_16x16x32_bf16 v[44:47], v[92:95], v[96:99], v[44:47]
	s_andn2_b64 s[76:77], s[76:77], exec
	s_waitcnt lgkmcnt(3)
	v_mfma_f32_16x16x32_bf16 v[44:47], v[100:103], v[104:107], v[44:47]
	v_mov_b32_e32 v41, v43
	s_waitcnt lgkmcnt(0)
	v_mfma_f32_16x16x32_bf16 v[44:47], v[108:111], v[112:115], v[44:47]
	s_nop 7
	v_cvt_pk_bf16_f32 v44, v44, v45
	v_cvt_pk_bf16_f32 v45, v46, v47
	v_lshl_add_u64 v[46:47], s[24:25], 0, v[42:43]
	v_lshl_add_u64 v[46:47], v[46:47], 0, v[40:41]
	v_lshl_add_u64 v[46:47], v[46:47], 0, s[72:73]
	s_or_b64 exec, exec, s[0:1]
	s_and_saveexec_b64 s[0:1], s[76:77]
	s_cbranch_execnz .LBB0_924
	s_branch .LBB0_925

.LBB0_924:
	v_add_u32_e32 v80, v49, v40
	v_mad_u32_u24 v81, v135, s96, v51
	ds_read_b64_tr_b16 v[84:85], v80 offset:36864
	ds_read_b64_tr_b16 v[86:87], v80 offset:37440
	ds_read_b128 v[88:91], v81 offset:4608
	ds_read_b64_tr_b16 v[92:93], v80 offset:41472
	ds_read_b64_tr_b16 v[94:95], v80 offset:42048
	ds_read_b128 v[96:99], v81 offset:4672
	v_lshlrev_b32_e32 v80, 5, v59
	v_lshlrev_b32_e32 v81, 1, v50
	v_add3_u32 v82, v48, v80, v81
	ds_read_b64_tr_b16 v[100:101], v82 offset:46080
	ds_read_b64_tr_b16 v[102:103], v82 offset:46656
	ds_read_b64_tr_b16 v[104:105], v49 offset:55360
	ds_read_b64_tr_b16 v[106:107], v49 offset:55936
	ds_read_b64_tr_b16 v[108:109], v82 offset:50688
	s_add_u32 s24, s56, s6
	s_addc_u32 s25, s57, s7
	s_waitcnt lgkmcnt(8)
	v_mfma_f32_16x16x32_bf16 v[44:47], v[84:87], v[88:91], 0
	ds_read_b64_tr_b16 v[110:111], v82 offset:51264
	ds_read_b64_tr_b16 v[80:81], v49 offset:59968
	ds_read_b64_tr_b16 v[82:83], v49 offset:60544
	s_waitcnt lgkmcnt(8)
	v_mfma_f32_16x16x32_bf16 v[44:47], v[92:95], v[96:99], v[44:47]
	s_waitcnt lgkmcnt(4)
	v_mfma_f32_16x16x32_bf16 v[44:47], v[100:103], v[104:107], v[44:47]
	v_mov_b32_e32 v41, v43
	s_waitcnt lgkmcnt(0)
	v_mfma_f32_16x16x32_bf16 v[44:47], v[108:111], v[80:83], v[44:47]
	s_nop 7
	v_cvt_pk_bf16_f32 v44, v44, v45
	v_cvt_pk_bf16_f32 v45, v46, v47
	v_lshl_add_u64 v[46:47], s[24:25], 0, v[42:43]
	v_lshl_add_u64 v[46:47], v[46:47], 0, v[40:41]
	v_lshl_add_u64 v[46:47], v[46:47], 0, s[72:73]

.LBB0_926:
	s_andn2_saveexec_b64 s[0:1], s[8:9]
	s_cbranch_execz .LBB0_928
	ds_read_b128 v[80:83], v62
	ds_read_b64_tr_b16 v[84:85], v58 offset:36928
	ds_read_b64_tr_b16 v[86:87], v58 offset:37504
	ds_read_b128 v[88:91], v62 offset:64
	ds_read_b64_tr_b16 v[92:93], v58 offset:41536
	ds_read_b64_tr_b16 v[94:95], v58 offset:42112
	s_add_u32 s8, s54, s6
	s_addc_u32 s9, s55, s7
	v_mov_b32_e32 v41, v43
	s_waitcnt lgkmcnt(3)
	v_mfma_f32_16x16x32_bf16 v[44:47], v[80:83], v[84:87], 0
	s_waitcnt lgkmcnt(0)
	v_mfma_f32_16x16x32_bf16 v[44:47], v[88:91], v[92:95], v[44:47]
	s_nop 7
	v_cvt_pk_bf16_f32 v44, v44, v45
	v_cvt_pk_bf16_f32 v45, v46, v47
	v_lshl_add_u64 v[46:47], s[8:9], 0, v[42:43]
	v_lshl_add_u64 v[46:47], v[46:47], 0, v[40:41]
	v_lshl_add_u64 v[46:47], v[46:47], 0, s[72:73]
.LBB0_928:
	s_or_b64 exec, exec, s[0:1]
	v_mov_b32_e32 v61, v43
	v_lshl_add_u64 v[46:47], v[46:47], 0, v[60:61]
	global_store_dwordx2 v[46:47], v[44:45], off nt
	s_and_saveexec_b64 s[0:1], vcc
	s_xor_b64 s[0:1], exec, s[0:1]
	s_cbranch_execz .LBB0_940
	v_cmp_lt_i32_e32 vcc, 1, v55
	s_mov_b64 s[8:9], 0
	s_mov_b64 s[80:81], 0
	s_and_saveexec_b64 s[24:25], vcc
	s_xor_b64 s[76:77], exec, s[24:25]
	s_cbranch_execz .LBB0_935
	v_cmp_eq_u32_e32 vcc, 2, v55
	s_mov_b64 s[84:85], -1
	s_and_saveexec_b64 s[80:81], vcc
	s_cbranch_execz .LBB0_932
	v_mul_u32_u24_e32 v44, 0x48, v135
	v_lshlrev_b32_e32 v55, 1, v44
	v_mad_u32_u24 v80, v63, s96, v56
	v_add_u32_e32 v81, v52, v55
	ds_read_b128 v[84:87], v80
	ds_read_b128 v[88:91], v81 offset:6912
	ds_read_b128 v[92:95], v80 offset:64
	ds_read_b128 v[96:99], v81 offset:6976
	v_add_u32_e32 v80, 0, v55
	v_add3_u32 v81, v80, v40, v74
	ds_read_b64 v[82:83], v81 offset:34560
	s_waitcnt lgkmcnt(3)
	v_mfma_f32_16x16x32_bf16 v[44:47], v[84:87], v[88:91], 0
	s_waitcnt lgkmcnt(1)
	v_mfma_f32_16x16x32_bf16 v[44:47], v[92:95], v[96:99], v[44:47]
	s_add_u32 s24, s58, s6
	s_addc_u32 s25, s59, s7
	v_mov_b32_e32 v41, v43
	s_waitcnt lgkmcnt(0)
	v_and_b32_e32 v67, 0xffff0000, v82
	v_lshlrev_b32_e32 v66, 16, v82
	s_nop 1
	v_pk_add_f32 v[44:45], v[44:45], v[66:67]
	v_and_b32_e32 v67, 0xffff0000, v83
	v_lshlrev_b32_e32 v66, 16, v83
	v_pk_add_f32 v[46:47], v[46:47], v[66:67]
	v_cvt_pk_bf16_f32 v44, v44, v45
	v_cvt_pk_bf16_f32 v45, v46, v47
	v_lshl_add_u64 v[46:47], s[24:25], 0, v[42:43]
	v_lshl_add_u64 v[46:47], v[46:47], 0, v[40:41]
	v_lshl_add_u64 v[46:47], v[46:47], 0, s[74:75]
	s_xor_b64 s[84:85], exec, -1

.LBB0_934:
	v_mad_u32_u24 v80, v63, s96, v57
	v_mad_u32_u24 v81, v135, s96, v52
	ds_read_b128 v[84:87], v80
	ds_read_b128 v[88:91], v81 offset:6912
	ds_read_b128 v[92:95], v80 offset:64
	ds_read_b128 v[96:99], v81 offset:6976
	v_add_u32_e32 v80, v53, v40
	ds_read_b64_tr_b16 v[100:101], v80 offset:55296
	ds_read_b64_tr_b16 v[102:103], v80 offset:55872
	s_waitcnt lgkmcnt(4)
	v_mfma_f32_16x16x32_bf16 v[44:47], v[84:87], v[88:91], 0
	v_mad_u32_u24 v41, v135, s96, v54
	ds_read_b128 v[84:87], v41 offset:6912
	ds_read_b64_tr_b16 v[88:89], v80 offset:59904
	ds_read_b64_tr_b16 v[90:91], v80 offset:60480
	s_add_u32 s24, s60, s6
	s_waitcnt lgkmcnt(5)
	v_mfma_f32_16x16x32_bf16 v[44:47], v[92:95], v[96:99], v[44:47]
	s_addc_u32 s25, s61, s7
	s_andn2_b64 s[8:9], s[8:9], exec
	s_waitcnt lgkmcnt(2)
	v_mfma_f32_16x16x32_bf16 v[44:47], v[100:103], v[84:87], v[44:47]
	ds_read_b128 v[62:65], v41 offset:6976
	v_mov_b32_e32 v41, v43
	s_waitcnt lgkmcnt(0)
	v_mfma_f32_16x16x32_bf16 v[44:47], v[88:91], v[62:65], v[44:47]
	s_nop 7
	v_cvt_pk_bf16_f32 v44, v44, v45
	v_cvt_pk_bf16_f32 v45, v46, v47
	v_lshl_add_u64 v[46:47], s[24:25], 0, v[42:43]
	v_lshl_add_u64 v[46:47], v[46:47], 0, v[40:41]
	v_lshl_add_u64 v[46:47], v[46:47], 0, s[74:75]
	s_or_b64 exec, exec, s[76:77]
	s_and_saveexec_b64 s[76:77], s[8:9]
	s_cbranch_execnz .LBB0_938
	s_branch .LBB0_939

.LBB0_938:
	v_mad_u32_u24 v41, v135, s96, v51
	v_add_u32_e32 v80, v49, v40
	ds_read_b64_tr_b16 v[84:85], v80 offset:36864
	ds_read_b64_tr_b16 v[86:87], v80 offset:37440
	ds_read_b128 v[88:91], v41 offset:6912
	v_lshlrev_b32_e32 v81, 1, v50
	ds_read_b64_tr_b16 v[92:93], v80 offset:41472
	ds_read_b64_tr_b16 v[94:95], v80 offset:42048
	v_lshlrev_b32_e32 v80, 5, v59
	v_add3_u32 v82, v48, v80, v81
	ds_read_b64_tr_b16 v[96:97], v82 offset:46080
	ds_read_b64_tr_b16 v[98:99], v82 offset:46656
	ds_read_b64_tr_b16 v[100:101], v49 offset:55392
	ds_read_b64_tr_b16 v[102:103], v49 offset:55968
	ds_read_b64_tr_b16 v[104:105], v82 offset:50688
	ds_read_b64_tr_b16 v[106:107], v82 offset:51264
	s_add_u32 s8, s56, s6
	s_addc_u32 s9, s57, s7
	s_waitcnt lgkmcnt(8)
	v_mfma_f32_16x16x32_bf16 v[44:47], v[84:87], v[88:91], 0
	ds_read_b64_tr_b16 v[80:81], v49 offset:60000
	ds_read_b64_tr_b16 v[82:83], v49 offset:60576
	ds_read_b128 v[62:65], v41 offset:6976
	s_waitcnt lgkmcnt(0)
	v_mfma_f32_16x16x32_bf16 v[44:47], v[92:95], v[62:65], v[44:47]
	v_mfma_f32_16x16x32_bf16 v[44:47], v[96:99], v[100:103], v[44:47]
	v_mov_b32_e32 v41, v43
	v_mfma_f32_16x16x32_bf16 v[44:47], v[104:107], v[80:83], v[44:47]
	s_nop 7
	v_cvt_pk_bf16_f32 v44, v44, v45
	v_cvt_pk_bf16_f32 v45, v46, v47
	v_lshl_add_u64 v[46:47], s[8:9], 0, v[42:43]
	v_lshl_add_u64 v[40:41], v[46:47], 0, v[40:41]
	v_lshl_add_u64 v[46:47], v[40:41], 0, s[74:75]

.LBB0_940:
	s_andn2_saveexec_b64 s[0:1], s[0:1]
	s_cbranch_execz .LBB0_772
	ds_read_b128 v[80:83], v62
	ds_read_b64_tr_b16 v[84:85], v58 offset:36960
	ds_read_b64_tr_b16 v[86:87], v58 offset:37536
	ds_read_b128 v[88:91], v62 offset:64
	ds_read_b64_tr_b16 v[92:93], v58 offset:41568
	ds_read_b64_tr_b16 v[94:95], v58 offset:42144
	s_add_u32 s6, s54, s6
	s_addc_u32 s7, s55, s7
	v_mov_b32_e32 v41, v43
	s_waitcnt lgkmcnt(3)
	v_mfma_f32_16x16x32_bf16 v[44:47], v[80:83], v[84:87], 0
	s_waitcnt lgkmcnt(0)
	v_mfma_f32_16x16x32_bf16 v[44:47], v[88:91], v[92:95], v[44:47]
	s_nop 7
	v_cvt_pk_bf16_f32 v44, v44, v45
	v_cvt_pk_bf16_f32 v45, v46, v47
	v_lshl_add_u64 v[46:47], s[6:7], 0, v[42:43]
	v_lshl_add_u64 v[40:41], v[46:47], 0, v[40:41]
	v_lshl_add_u64 v[46:47], v[40:41], 0, s[74:75]
	s_branch .LBB0_772
